# attention: trailing half (waves 4-7) issues the MFMA-segment's first LDS fragment reads before its tile barrier (latency hidden in the barrier wait)
# baseline (speedup 1.0000x reference)
; #define SBAR() __builtin_amdgcn_sched_barrier(0)
; #define ABAR() asm volatile("s_waitcnt lgkmcnt(0)\n\ts_barrier" ::: "memory")
; __device__ __forceinline__ void qkt2(f32x4a (&s)[4][2], const char* Ks, int ko0, int ko1, const bf16x8 (&qr)[2][2]) {
;   const f32x4a z4 = {0.f, 0.f, 0.f, 0.f};
; #pragma unroll
;   for (int h2 = 0; h2 < 2; ++h2) { bf16x8 kf[2][2];
; #pragma unroll
;     for (int k2 = 0; k2 < 2; ++k2) { kf[k2][0] = *reinterpret_cast<const bf16x8*>(Ks + ko0 + 2048 * (2 * h2 + k2)); kf[k2][1] = *reinterpret_cast<const bf16x8*>(Ks + ko1 + 2048 * (2 * h2 + k2)); }
; __device__ __forceinline__ void attn_unit(int h, int qb_, const Tensors& T, char* lds, LASP unsigned char* ldsl, int tid_in) {
;     ...
;       if (hf) { asm volatile("s_waitcnt vmcnt(6)" ::: "memory"); ABAR(); }
;       { const int vbt = vb0 + sgv * STGB; const int sgk = sgv == NSTG - 1 ? 0 : sgv + 1; __builtin_amdgcn_s_setprio(1);
;         vread<0>(va, vbt); SBAR();
;         if (t + 1 < 2 * NT) qkt2(s, lds + sgk * STGB, ko0, ko1, qr);
.LBB0_571:
	v_exp_f32_e32 v195, v56
	v_exp_f32_e32 v193, v57
	v_exp_f32_e32 v191, v58
	v_exp_f32_e32 v187, v59
	v_exp_f32_e32 v194, v60
	v_exp_f32_e32 v192, v61
	v_exp_f32_e32 v190, v62
	v_exp_f32_e32 v186, v63
	v_exp_f32_e32 v189, v64
	v_exp_f32_e32 v185, v65
	v_exp_f32_e32 v175, v66
	v_exp_f32_e32 v171, v67
	v_exp_f32_e32 v188, v68
	v_exp_f32_e32 v184, v69
	v_exp_f32_e32 v174, v70
	v_exp_f32_e32 v170, v71
	v_exp_f32_e32 v173, v80
	v_exp_f32_e32 v169, v81
	v_exp_f32_e32 v167, v82
	v_exp_f32_e32 v163, v83
	v_exp_f32_e32 v172, v88
	v_exp_f32_e32 v168, v89
	v_exp_f32_e32 v166, v90
	v_exp_f32_e32 v162, v91
	v_exp_f32_e32 v165, v92
	v_exp_f32_e32 v161, v93
	v_exp_f32_e32 v159, v94
	v_exp_f32_e32 v157, v95
	v_exp_f32_e32 v164, v96
	v_exp_f32_e32 v160, v97
	v_exp_f32_e32 v158, v98
	v_exp_f32_e32 v156, v99
	s_setprio 1
	s_andn2_b64 vcc, exec, s[40:41]
	v_cvt_pk_bf16_f32 v116, v195, v193
	v_cvt_pk_bf16_f32 v117, v191, v187
	v_cvt_pk_bf16_f32 v118, v189, v185
	v_cvt_pk_bf16_f32 v119, v175, v171
	v_cvt_pk_bf16_f32 v112, v173, v169
	v_cvt_pk_bf16_f32 v113, v167, v163
	v_cvt_pk_bf16_f32 v114, v165, v161
	v_cvt_pk_bf16_f32 v115, v159, v157
	v_cvt_pk_bf16_f32 v124, v194, v192
	v_cvt_pk_bf16_f32 v125, v190, v186
	v_cvt_pk_bf16_f32 v126, v188, v184
	v_cvt_pk_bf16_f32 v127, v174, v170
	v_cvt_pk_bf16_f32 v120, v172, v168
	v_cvt_pk_bf16_f32 v121, v166, v162
	v_cvt_pk_bf16_f32 v122, v164, v160
	v_cvt_pk_bf16_f32 v123, v158, v156
	s_cbranch_vccnz .LBB0_573
	s_mul_i32 s4, s43, 0x6000
	v_add_u32_e32 v238, s4, v232
	s_add_i32 s4, s43, 1
	s_cmp_lg_u32 s43, 5
	s_cselect_b32 s43, s4, 0
	ds_read_b64_tr_b16 v[136:137], v238 offset:0
	ds_read_b64_tr_b16 v[138:139], v238 offset:0x200
	ds_read_b64_tr_b16 v[128:129], v238 offset:0x400
	ds_read_b64_tr_b16 v[130:131], v238 offset:0x600
	ds_read_b64_tr_b16 v[140:141], v238 offset:0x800
	ds_read_b64_tr_b16 v[142:143], v238 offset:0xa00
	ds_read_b64_tr_b16 v[132:133], v238 offset:0xc00
	ds_read_b64_tr_b16 v[134:135], v238 offset:0xe00
	s_mul_i32 s4, s43, 0x6000
	s_add_i32 s4, s4, 0
	v_add_u32_e32 v178, s4, v205
	v_add_u32_e32 v179, s4, v206
	ds_read_b128 v[56:59], v178
	ds_read_b128 v[60:63], v178 offset:2048
	ds_read_b128 v[64:67], v179
	ds_read_b128 v[68:71], v179 offset:2048
	s_waitcnt vmcnt(6)
	s_waitcnt lgkmcnt(0)
	s_barrier
	s_branch .Lattn_xgo
.LBB0_573:
	s_mul_i32 s4, s43, 0x6000
	v_add_u32_e32 v238, s4, v232
	s_add_i32 s4, s43, 1
	s_cmp_lg_u32 s43, 5
	s_cselect_b32 s43, s4, 0
	ds_read_b64_tr_b16 v[136:137], v238 offset:0
	ds_read_b64_tr_b16 v[138:139], v238 offset:0x200
	ds_read_b64_tr_b16 v[128:129], v238 offset:0x400
	ds_read_b64_tr_b16 v[130:131], v238 offset:0x600
	ds_read_b64_tr_b16 v[140:141], v238 offset:0x800
	ds_read_b64_tr_b16 v[142:143], v238 offset:0xa00
	ds_read_b64_tr_b16 v[132:133], v238 offset:0xc00
	ds_read_b64_tr_b16 v[134:135], v238 offset:0xe00
	s_mul_i32 s4, s43, 0x6000
	s_add_i32 s4, s4, 0
	v_add_u32_e32 v178, s4, v205
	v_add_u32_e32 v179, s4, v206
	ds_read_b128 v[56:59], v178
	ds_read_b128 v[60:63], v178 offset:2048
	ds_read_b128 v[64:67], v179
	ds_read_b128 v[68:71], v179 offset:2048
; #define SBAR() __builtin_amdgcn_sched_barrier(0)
; #define MM16(A_, B_, C_) __builtin_amdgcn_mfma_f32_16x16x32_bf16(A_, B_, C_, 0, 0, 0)
; __device__ __forceinline__ void qkt2(f32x4a (&s)[4][2], const char* Ks, int ko0, int ko1, const bf16x8 (&qr)[2][2]) {
;   const f32x4a z4 = {0.f, 0.f, 0.f, 0.f};
; #pragma unroll
;   for (int h2 = 0; h2 < 2; ++h2) { bf16x8 kf[2][2];
; #pragma unroll
;     for (int k2 = 0; k2 < 2; ++k2) { kf[k2][0] = *reinterpret_cast<const bf16x8*>(Ks + ko0 + 2048 * (2 * h2 + k2)); kf[k2][1] = *reinterpret_cast<const bf16x8*>(Ks + ko1 + 2048 * (2 * h2 + k2)); }
;     SBAR();
; #pragma unroll
;     for (int k2 = 0; k2 < 2; ++k2)
; #pragma unroll
;       for (int qb = 0; qb < 2; ++qb) s[2 * h2 + k2][qb] = MM16(kf[k2][0], qr[qb][0], z4);
; #pragma unroll
;     for (int k2 = 0; k2 < 2; ++k2)
; #pragma unroll
;       for (int qb = 0; qb < 2; ++qb) s[2 * h2 + k2][qb] = MM16(kf[k2][1], qr[qb][1], s[2 * h2 + k2][qb]);
;     SBAR(); }
; __device__ __forceinline__ void finishSM(f32x4a (&s)[4][2], float& l0, float& l1, bf16x8 (&pa)[2][2]) {
;     ...
;   float a0 = 0.f, a1 = 0.f, a2 = 0.f, a3 = 0.f, b0 = 0.f, b1 = 0.f, b2 = 0.f, b3 = 0.f;
; #pragma unroll
;   for (int kb = 0; kb < 4; ++kb) { a0 += s[kb][0][0]; a1 += s[kb][0][1]; a2 += s[kb][0][2]; a3 += s[kb][0][3]; b0 += s[kb][1][0]; b1 += s[kb][1][1]; b2 += s[kb][1][2]; b3 += s[kb][1][3]; }
;   l0 += (a0 + a1) + (a2 + a3); l1 += (b0 + b1) + (b2 + b3);
.Lattn_xgo:
	s_cmpk_eq_i32 s44, 0xff
	s_cbranch_scc1 .LBB0_575
	s_waitcnt lgkmcnt(0)
	v_mfma_f32_16x16x32_bf16 v[80:83], v[56:59], v[4:7], 0
	v_add_f32_e32 v188, v188, v194
	v_add_f32_e32 v189, v189, v195
	v_mfma_f32_16x16x32_bf16 v[88:91], v[56:59], v[12:15], 0
	v_add_f32_e32 v184, v184, v192
	v_add_f32_e32 v185, v185, v193
	v_mfma_f32_16x16x32_bf16 v[92:95], v[60:63], v[4:7], 0
	v_add_f32_e32 v174, v174, v190
	v_add_f32_e32 v175, v175, v191
	v_mfma_f32_16x16x32_bf16 v[96:99], v[60:63], v[12:15], 0
	v_add_f32_e32 v170, v170, v186
	v_add_f32_e32 v171, v171, v187
	v_mfma_f32_16x16x32_bf16 v[56:59], v[64:67], v[8:11], v[80:83]
	v_add_f32_e32 v172, v172, v188
	v_add_f32_e32 v173, v173, v189
	v_mfma_f32_16x16x32_bf16 v[60:63], v[64:67], v[16:19], v[88:91]
	v_add_f32_e32 v168, v168, v184
	v_add_f32_e32 v169, v169, v185
	v_mfma_f32_16x16x32_bf16 v[64:67], v[68:71], v[8:11], v[92:95]
	v_add_f32_e32 v166, v166, v174
	v_add_f32_e32 v167, v167, v175
	v_mfma_f32_16x16x32_bf16 v[68:71], v[68:71], v[16:19], v[96:99]
	v_add_f32_e32 v162, v162, v170
	v_add_f32_e32 v163, v163, v171
	s_nop 0
	ds_read_b128 v[80:83], v178 offset:4096
	ds_read_b128 v[88:91], v178 offset:6144
	ds_read_b128 v[92:95], v179 offset:4096
	ds_read_b128 v[96:99], v179 offset:6144
	s_waitcnt lgkmcnt(3)
	v_mfma_f32_16x16x32_bf16 v[240:243], v[80:83], v[4:7], 0
	v_add_f32_e32 v164, v164, v172
	v_add_f32_e32 v165, v165, v173
	v_mfma_f32_16x16x32_bf16 v[244:247], v[80:83], v[12:15], 0
	v_add_f32_e32 v160, v160, v168
	v_add_f32_e32 v161, v161, v169
	s_waitcnt lgkmcnt(2)
	v_mfma_f32_16x16x32_bf16 v[248:251], v[88:91], v[4:7], 0
	v_add_f32_e32 v158, v158, v166
	v_add_f32_e32 v159, v159, v167
	v_mfma_f32_16x16x32_bf16 v[228:231], v[88:91], v[12:15], 0
	v_add_f32_e32 v156, v156, v162
	v_add_f32_e32 v157, v157, v163
	s_waitcnt lgkmcnt(1)
	v_mfma_f32_16x16x32_bf16 v[80:83], v[92:95], v[8:11], v[240:243]
	v_add_f32_e32 v160, v164, v160
	v_add_f32_e32 v161, v165, v161
	v_mfma_f32_16x16x32_bf16 v[88:91], v[92:95], v[16:19], v[244:247]
	v_add_f32_e32 v156, v158, v156
	v_add_f32_e32 v157, v159, v157
	s_waitcnt lgkmcnt(0)
	v_mfma_f32_16x16x32_bf16 v[92:95], v[96:99], v[8:11], v[248:251]
	v_add_f32_e32 v156, v160, v156
	v_add_f32_e32 v157, v161, v157
	v_mfma_f32_16x16x32_bf16 v[96:99], v[96:99], v[16:19], v[228:231]
	v_add_f32_e32 v154, v154, v156
	v_add_f32_e32 v155, v155, v157
	s_branch .LBB0_576
.LBB0_575:
	s_waitcnt lgkmcnt(0)
	v_mov_b32_e32 v56, v195
	v_mov_b32_e32 v57, v193
	v_mov_b32_e32 v58, v191
	v_mov_b32_e32 v59, v187
	v_mov_b32_e32 v60, v194
	v_mov_b32_e32 v61, v192
	v_mov_b32_e32 v62, v190
	v_mov_b32_e32 v63, v186
	v_mov_b32_e32 v64, v189
	v_mov_b32_e32 v65, v185
	v_mov_b32_e32 v66, v175
	v_mov_b32_e32 v67, v171
	v_mov_b32_e32 v68, v188
	v_mov_b32_e32 v69, v184
	v_mov_b32_e32 v70, v174
	v_mov_b32_e32 v71, v170
	v_mov_b32_e32 v80, v173
	v_mov_b32_e32 v81, v169
	v_mov_b32_e32 v82, v167
	v_mov_b32_e32 v83, v163
	v_mov_b32_e32 v88, v172
	v_mov_b32_e32 v89, v168
	v_mov_b32_e32 v90, v166
	v_mov_b32_e32 v91, v162
	v_mov_b32_e32 v92, v165
	v_mov_b32_e32 v93, v161
	v_mov_b32_e32 v94, v159
	v_mov_b32_e32 v95, v157
	v_mov_b32_e32 v96, v164
	v_mov_b32_e32 v97, v160
	v_mov_b32_e32 v98, v158
	v_mov_b32_e32 v99, v156
	v_add_f32_e32 v188, v188, v194
	v_add_f32_e32 v189, v189, v195
	v_add_f32_e32 v184, v184, v192
	v_add_f32_e32 v185, v185, v193
	v_add_f32_e32 v174, v174, v190
	v_add_f32_e32 v175, v175, v191
	v_add_f32_e32 v170, v170, v186
	v_add_f32_e32 v171, v171, v187
	v_add_f32_e32 v172, v172, v188
	v_add_f32_e32 v173, v173, v189
	v_add_f32_e32 v168, v168, v184
	v_add_f32_e32 v169, v169, v185
	v_add_f32_e32 v166, v166, v174
	v_add_f32_e32 v167, v167, v175
	v_add_f32_e32 v162, v162, v170
	v_add_f32_e32 v163, v163, v171
	v_add_f32_e32 v164, v164, v172
	v_add_f32_e32 v165, v165, v173
	v_add_f32_e32 v160, v160, v168
	v_add_f32_e32 v161, v161, v169
	v_add_f32_e32 v158, v158, v166
	v_add_f32_e32 v159, v159, v167
	v_add_f32_e32 v156, v156, v162
	v_add_f32_e32 v157, v157, v163
	v_add_f32_e32 v160, v164, v160
	v_add_f32_e32 v161, v165, v161
	v_add_f32_e32 v156, v158, v156
	v_add_f32_e32 v157, v159, v157
	v_add_f32_e32 v156, v160, v156
	v_add_f32_e32 v157, v161, v157
	v_add_f32_e32 v154, v154, v156
	v_add_f32_e32 v155, v155, v157
